# attn0 per-wave compute rewritten: all window score tiles first, one row max / exp pass over the 160-key window (no online rescaling), then all PV MFMAs
# speedup vs baseline: 1.0039x; 1.0039x over previous
.LBB0_444:
	s_waitcnt vmcnt(0)
	s_barrier
	s_add_i32 s85, s74, s71
	v_mov_b32_e32 v68, v238
	v_xor_b32_e32 v155, 32, v238
	v_and_b32_e32 v156, 64, v238
	v_add_u32_e32 v156, 64, v156
	v_cmp_lt_i32_e32 vcc, v155, v156
	s_nop 1
	v_cndmask_b32_e32 v157, v238, v155, vcc
	v_lshlrev_b32_e32 v157, 2, v157
	s_cmp_lt_i32 s85, 4
	s_cbranch_scc1 .La0_miss0
	s_add_i32 s68, s72, 12
	s_and_b32 s68, s68, 15
	s_lshl_b32 s68, s68, 13
	v_add_u32_e32 v158, s68, v152
	ds_read_b128 v[48:51], v158
	ds_read_b128 v[52:55], v158 offset:1024
	ds_read_b128 v[56:59], v158 offset:2048
	ds_read_b128 v[60:63], v158 offset:3072
	s_waitcnt lgkmcnt(3)
	v_mfma_f32_32x32x16_bf16 v[160:175], v[48:51], v[92:95], 0
	s_waitcnt lgkmcnt(2)
	v_mfma_f32_32x32x16_bf16 v[160:175], v[52:55], v[88:91], v[160:175]
	s_waitcnt lgkmcnt(1)
	v_mfma_f32_32x32x16_bf16 v[160:175], v[56:59], v[84:87], v[160:175]
	s_waitcnt lgkmcnt(0)
	v_mfma_f32_32x32x16_bf16 v[160:175], v[60:63], v[80:83], v[160:175]
	s_branch .La0_have0
.La0_miss0:
	v_mov_b32_e32 v160, v239
	v_mov_b32_e32 v161, v239
	v_mov_b32_e32 v162, v239
	v_mov_b32_e32 v163, v239
	v_mov_b32_e32 v164, v239
	v_mov_b32_e32 v165, v239
	v_mov_b32_e32 v166, v239
	v_mov_b32_e32 v167, v239
	v_mov_b32_e32 v168, v239
	v_mov_b32_e32 v169, v239
	v_mov_b32_e32 v170, v239
	v_mov_b32_e32 v171, v239
	v_mov_b32_e32 v172, v239
	v_mov_b32_e32 v173, v239
	v_mov_b32_e32 v174, v239
	v_mov_b32_e32 v175, v239
.La0_have0:
	s_cmp_lt_i32 s85, 3
	s_cbranch_scc1 .La0_miss1
	s_add_i32 s68, s72, 13
	s_and_b32 s68, s68, 15
	s_lshl_b32 s68, s68, 13
	v_add_u32_e32 v158, s68, v152
	ds_read_b128 v[224:227], v158
	ds_read_b128 v[228:231], v158 offset:1024
	ds_read_b128 v[2:5], v158 offset:2048
	ds_read_b128 v[8:11], v158 offset:3072
	s_waitcnt lgkmcnt(3)
	v_mfma_f32_32x32x16_bf16 v[176:191], v[224:227], v[92:95], 0
	s_waitcnt lgkmcnt(2)
	v_mfma_f32_32x32x16_bf16 v[176:191], v[228:231], v[88:91], v[176:191]
	s_waitcnt lgkmcnt(1)
	v_mfma_f32_32x32x16_bf16 v[176:191], v[2:5], v[84:87], v[176:191]
	s_waitcnt lgkmcnt(0)
	v_mfma_f32_32x32x16_bf16 v[176:191], v[8:11], v[80:83], v[176:191]
	s_branch .La0_have1
.La0_miss1:
	v_mov_b32_e32 v176, v239
	v_mov_b32_e32 v177, v239
	v_mov_b32_e32 v178, v239
	v_mov_b32_e32 v179, v239
	v_mov_b32_e32 v180, v239
	v_mov_b32_e32 v181, v239
	v_mov_b32_e32 v182, v239
	v_mov_b32_e32 v183, v239
	v_mov_b32_e32 v184, v239
	v_mov_b32_e32 v185, v239
	v_mov_b32_e32 v186, v239
	v_mov_b32_e32 v187, v239
	v_mov_b32_e32 v188, v239
	v_mov_b32_e32 v189, v239
	v_mov_b32_e32 v190, v239
	v_mov_b32_e32 v191, v239
.La0_have1:
	s_cmp_lt_i32 s85, 2
	s_cbranch_scc1 .La0_miss2
	s_add_i32 s68, s72, 14
	s_and_b32 s68, s68, 15
	s_lshl_b32 s68, s68, 13
	v_add_u32_e32 v158, s68, v152
	ds_read_b128 v[48:51], v158
	ds_read_b128 v[52:55], v158 offset:1024
	ds_read_b128 v[56:59], v158 offset:2048
	ds_read_b128 v[60:63], v158 offset:3072
	s_waitcnt lgkmcnt(3)
	v_mfma_f32_32x32x16_bf16 v[192:207], v[48:51], v[92:95], 0
	s_waitcnt lgkmcnt(2)
	v_mfma_f32_32x32x16_bf16 v[192:207], v[52:55], v[88:91], v[192:207]
	s_waitcnt lgkmcnt(1)
	v_mfma_f32_32x32x16_bf16 v[192:207], v[56:59], v[84:87], v[192:207]
	s_waitcnt lgkmcnt(0)
	v_mfma_f32_32x32x16_bf16 v[192:207], v[60:63], v[80:83], v[192:207]
	s_branch .La0_have2
.La0_miss2:
	v_mov_b32_e32 v192, v239
	v_mov_b32_e32 v193, v239
	v_mov_b32_e32 v194, v239
	v_mov_b32_e32 v195, v239
	v_mov_b32_e32 v196, v239
	v_mov_b32_e32 v197, v239
	v_mov_b32_e32 v198, v239
	v_mov_b32_e32 v199, v239
	v_mov_b32_e32 v200, v239
	v_mov_b32_e32 v201, v239
	v_mov_b32_e32 v202, v239
	v_mov_b32_e32 v203, v239
	v_mov_b32_e32 v204, v239
	v_mov_b32_e32 v205, v239
	v_mov_b32_e32 v206, v239
	v_mov_b32_e32 v207, v239
.La0_have2:
	s_cmp_lt_i32 s85, 1
	s_cbranch_scc1 .La0_miss3
	s_add_i32 s68, s72, 15
	s_and_b32 s68, s68, 15
	s_lshl_b32 s68, s68, 13
	v_add_u32_e32 v158, s68, v152
	ds_read_b128 v[224:227], v158
	ds_read_b128 v[228:231], v158 offset:1024
	ds_read_b128 v[2:5], v158 offset:2048
	ds_read_b128 v[8:11], v158 offset:3072
	s_waitcnt lgkmcnt(3)
	v_mfma_f32_32x32x16_bf16 v[208:223], v[224:227], v[92:95], 0
	s_waitcnt lgkmcnt(2)
	v_mfma_f32_32x32x16_bf16 v[208:223], v[228:231], v[88:91], v[208:223]
	s_waitcnt lgkmcnt(1)
	v_mfma_f32_32x32x16_bf16 v[208:223], v[2:5], v[84:87], v[208:223]
	s_waitcnt lgkmcnt(0)
	v_mfma_f32_32x32x16_bf16 v[208:223], v[8:11], v[80:83], v[208:223]
	s_branch .La0_have3
.La0_miss3:
	v_mov_b32_e32 v208, v239
	v_mov_b32_e32 v209, v239
	v_mov_b32_e32 v210, v239
	v_mov_b32_e32 v211, v239
	v_mov_b32_e32 v212, v239
	v_mov_b32_e32 v213, v239
	v_mov_b32_e32 v214, v239
	v_mov_b32_e32 v215, v239
	v_mov_b32_e32 v216, v239
	v_mov_b32_e32 v217, v239
	v_mov_b32_e32 v218, v239
	v_mov_b32_e32 v219, v239
	v_mov_b32_e32 v220, v239
	v_mov_b32_e32 v221, v239
	v_mov_b32_e32 v222, v239
	v_mov_b32_e32 v223, v239
.La0_have3:
	s_add_i32 s68, s72, 16
	s_and_b32 s68, s68, 15
	s_lshl_b32 s68, s68, 13
	v_add_u32_e32 v158, s68, v152
	ds_read_b128 v[48:51], v158
	ds_read_b128 v[52:55], v158 offset:1024
	ds_read_b128 v[56:59], v158 offset:2048
	ds_read_b128 v[60:63], v158 offset:3072
	s_waitcnt lgkmcnt(3)
	v_mfma_f32_32x32x16_bf16 v[96:111], v[48:51], v[92:95], 0
	s_waitcnt lgkmcnt(2)
	v_mfma_f32_32x32x16_bf16 v[96:111], v[52:55], v[88:91], v[96:111]
	s_waitcnt lgkmcnt(1)
	v_mfma_f32_32x32x16_bf16 v[96:111], v[56:59], v[84:87], v[96:111]
	s_waitcnt lgkmcnt(0)
	v_mfma_f32_32x32x16_bf16 v[96:111], v[60:63], v[80:83], v[96:111]
	s_nop 7
	s_nop 4
	v_cndmask_b32_e64 v160, v160, v239, s[6:7]
	v_cndmask_b32_e64 v161, v161, v239, s[38:39]
	v_cndmask_b32_e64 v162, v162, v239, s[40:41]
	v_cndmask_b32_e64 v163, v163, v239, s[42:43]
	v_cndmask_b32_e64 v164, v164, v239, s[44:45]
	v_cndmask_b32_e64 v165, v165, v239, s[46:47]
	v_cndmask_b32_e64 v166, v166, v239, s[48:49]
	v_cndmask_b32_e64 v167, v167, v239, s[50:51]
	v_cndmask_b32_e64 v168, v168, v239, s[52:53]
	v_cndmask_b32_e64 v169, v169, v239, s[54:55]
	v_cndmask_b32_e64 v170, v170, v239, s[56:57]
	v_cndmask_b32_e64 v171, v171, v239, s[58:59]
	v_cndmask_b32_e64 v172, v172, v239, s[60:61]
	v_cndmask_b32_e64 v173, v173, v239, s[62:63]
	v_cndmask_b32_e64 v174, v174, v239, s[64:65]
	v_cndmask_b32_e64 v175, v175, v239, s[66:67]
	v_cndmask_b32_e64 v96, v96, v239, s[4:5]
	v_cndmask_b32_e64 v97, v239, v97, s[6:7]
	v_cndmask_b32_e64 v98, v98, v239, s[8:9]
	v_cndmask_b32_e64 v99, v99, v239, s[10:11]
	v_cndmask_b32_e64 v100, v100, v239, s[12:13]
	v_cndmask_b32_e64 v101, v101, v239, s[14:15]
	v_cndmask_b32_e64 v102, v102, v239, s[16:17]
	v_cndmask_b32_e64 v103, v103, v239, s[18:19]
	v_cndmask_b32_e64 v104, v104, v239, s[20:21]
	v_cndmask_b32_e64 v105, v105, v239, s[22:23]
	v_cndmask_b32_e64 v106, v106, v239, s[24:25]
	v_cndmask_b32_e64 v107, v107, v239, s[26:27]
	v_cndmask_b32_e64 v108, v108, v239, s[28:29]
	v_cndmask_b32_e64 v109, v109, v239, s[30:31]
	v_cndmask_b32_e64 v110, v110, v239, s[34:35]
	v_cndmask_b32_e64 v111, v111, v239, s[36:37]
	v_max3_f32 v12, v160, v161, v162
	v_max3_f32 v13, v163, v164, v165
	v_max3_f32 v14, v166, v167, v168
	v_max3_f32 v15, v169, v170, v171
	v_max3_f32 v12, v12, v172, v173
	v_max3_f32 v13, v13, v174, v175
	v_max3_f32 v14, v14, v176, v177
	v_max3_f32 v15, v15, v178, v179
	v_max3_f32 v12, v12, v180, v181
	v_max3_f32 v13, v13, v182, v183
	v_max3_f32 v14, v14, v184, v185
	v_max3_f32 v15, v15, v186, v187
	v_max3_f32 v12, v12, v188, v189
	v_max3_f32 v13, v13, v190, v191
	v_max3_f32 v14, v14, v192, v193
	v_max3_f32 v15, v15, v194, v195
	v_max3_f32 v12, v12, v196, v197
	v_max3_f32 v13, v13, v198, v199
	v_max3_f32 v14, v14, v200, v201
	v_max3_f32 v15, v15, v202, v203
	v_max3_f32 v12, v12, v204, v205
	v_max3_f32 v13, v13, v206, v207
	v_max3_f32 v14, v14, v208, v209
	v_max3_f32 v15, v15, v210, v211
	v_max3_f32 v12, v12, v212, v213
	v_max3_f32 v13, v13, v214, v215
	v_max3_f32 v14, v14, v216, v217
	v_max3_f32 v15, v15, v218, v219
	v_max3_f32 v12, v12, v220, v221
	v_max3_f32 v13, v13, v222, v223
	v_max3_f32 v14, v14, v96, v97
	v_max3_f32 v15, v15, v98, v99
	v_max3_f32 v12, v12, v100, v101
	v_max3_f32 v13, v13, v102, v103
	v_max3_f32 v14, v14, v104, v105
	v_max3_f32 v15, v15, v106, v107
	v_max3_f32 v12, v12, v108, v109
	v_max3_f32 v13, v13, v110, v111
	v_max3_f32 v12, v12, v13, v14
	v_max_f32_e32 v12, v12, v15
	ds_bpermute_b32 v13, v157, v12
	s_waitcnt lgkmcnt(0)
	v_max_f32_e32 v1, v12, v13
	v_sub_f32_e32 v160, v160, v1
	v_sub_f32_e32 v161, v161, v1
	v_sub_f32_e32 v162, v162, v1
	v_sub_f32_e32 v163, v163, v1
	v_sub_f32_e32 v164, v164, v1
	v_sub_f32_e32 v165, v165, v1
	v_sub_f32_e32 v166, v166, v1
	v_sub_f32_e32 v167, v167, v1
	v_sub_f32_e32 v168, v168, v1
	v_sub_f32_e32 v169, v169, v1
	v_sub_f32_e32 v170, v170, v1
	v_sub_f32_e32 v171, v171, v1
	v_sub_f32_e32 v172, v172, v1
	v_sub_f32_e32 v173, v173, v1
	v_sub_f32_e32 v174, v174, v1
	v_sub_f32_e32 v175, v175, v1
	v_sub_f32_e32 v176, v176, v1
	v_sub_f32_e32 v177, v177, v1
	v_sub_f32_e32 v178, v178, v1
	v_sub_f32_e32 v179, v179, v1
	v_sub_f32_e32 v180, v180, v1
	v_sub_f32_e32 v181, v181, v1
	v_sub_f32_e32 v182, v182, v1
	v_sub_f32_e32 v183, v183, v1
	v_sub_f32_e32 v184, v184, v1
	v_sub_f32_e32 v185, v185, v1
	v_sub_f32_e32 v186, v186, v1
	v_sub_f32_e32 v187, v187, v1
	v_sub_f32_e32 v188, v188, v1
	v_sub_f32_e32 v189, v189, v1
	v_sub_f32_e32 v190, v190, v1
	v_sub_f32_e32 v191, v191, v1
	v_sub_f32_e32 v192, v192, v1
	v_sub_f32_e32 v193, v193, v1
	v_sub_f32_e32 v194, v194, v1
	v_sub_f32_e32 v195, v195, v1
	v_sub_f32_e32 v196, v196, v1
	v_sub_f32_e32 v197, v197, v1
	v_sub_f32_e32 v198, v198, v1
	v_sub_f32_e32 v199, v199, v1
	v_sub_f32_e32 v200, v200, v1
	v_sub_f32_e32 v201, v201, v1
	v_sub_f32_e32 v202, v202, v1
	v_sub_f32_e32 v203, v203, v1
	v_sub_f32_e32 v204, v204, v1
	v_sub_f32_e32 v205, v205, v1
	v_sub_f32_e32 v206, v206, v1
	v_sub_f32_e32 v207, v207, v1
	v_sub_f32_e32 v208, v208, v1
	v_sub_f32_e32 v209, v209, v1
	v_sub_f32_e32 v210, v210, v1
	v_sub_f32_e32 v211, v211, v1
	v_sub_f32_e32 v212, v212, v1
	v_sub_f32_e32 v213, v213, v1
	v_sub_f32_e32 v214, v214, v1
	v_sub_f32_e32 v215, v215, v1
	v_sub_f32_e32 v216, v216, v1
	v_sub_f32_e32 v217, v217, v1
	v_sub_f32_e32 v218, v218, v1
	v_sub_f32_e32 v219, v219, v1
	v_sub_f32_e32 v220, v220, v1
	v_sub_f32_e32 v221, v221, v1
	v_sub_f32_e32 v222, v222, v1
	v_sub_f32_e32 v223, v223, v1
	v_sub_f32_e32 v96, v96, v1
	v_sub_f32_e32 v97, v97, v1
	v_sub_f32_e32 v98, v98, v1
	v_sub_f32_e32 v99, v99, v1
	v_sub_f32_e32 v100, v100, v1
	v_sub_f32_e32 v101, v101, v1
	v_sub_f32_e32 v102, v102, v1
	v_sub_f32_e32 v103, v103, v1
	v_sub_f32_e32 v104, v104, v1
	v_sub_f32_e32 v105, v105, v1
	v_sub_f32_e32 v106, v106, v1
	v_sub_f32_e32 v107, v107, v1
	v_sub_f32_e32 v108, v108, v1
	v_sub_f32_e32 v109, v109, v1
	v_sub_f32_e32 v110, v110, v1
	v_sub_f32_e32 v111, v111, v1
	v_exp_f32_e32 v160, v160
	v_exp_f32_e32 v161, v161
	v_exp_f32_e32 v162, v162
	v_exp_f32_e32 v163, v163
	v_exp_f32_e32 v164, v164
	v_exp_f32_e32 v165, v165
	v_exp_f32_e32 v166, v166
	v_exp_f32_e32 v167, v167
	v_exp_f32_e32 v168, v168
	v_exp_f32_e32 v169, v169
	v_exp_f32_e32 v170, v170
	v_exp_f32_e32 v171, v171
	v_exp_f32_e32 v172, v172
	v_exp_f32_e32 v173, v173
	v_exp_f32_e32 v174, v174
	v_exp_f32_e32 v175, v175
	v_exp_f32_e32 v176, v176
	v_exp_f32_e32 v177, v177
	v_exp_f32_e32 v178, v178
	v_exp_f32_e32 v179, v179
	v_exp_f32_e32 v180, v180
	v_exp_f32_e32 v181, v181
	v_exp_f32_e32 v182, v182
	v_exp_f32_e32 v183, v183
	v_exp_f32_e32 v184, v184
	v_exp_f32_e32 v185, v185
	v_exp_f32_e32 v186, v186
	v_exp_f32_e32 v187, v187
	v_exp_f32_e32 v188, v188
	v_exp_f32_e32 v189, v189
	v_exp_f32_e32 v190, v190
	v_exp_f32_e32 v191, v191
	v_exp_f32_e32 v192, v192
	v_exp_f32_e32 v193, v193
	v_exp_f32_e32 v194, v194
	v_exp_f32_e32 v195, v195
	v_exp_f32_e32 v196, v196
	v_exp_f32_e32 v197, v197
	v_exp_f32_e32 v198, v198
	v_exp_f32_e32 v199, v199
	v_exp_f32_e32 v200, v200
	v_exp_f32_e32 v201, v201
	v_exp_f32_e32 v202, v202
	v_exp_f32_e32 v203, v203
	v_exp_f32_e32 v204, v204
	v_exp_f32_e32 v205, v205
	v_exp_f32_e32 v206, v206
	v_exp_f32_e32 v207, v207
	v_exp_f32_e32 v208, v208
	v_exp_f32_e32 v209, v209
	v_exp_f32_e32 v210, v210
	v_exp_f32_e32 v211, v211
	v_exp_f32_e32 v212, v212
	v_exp_f32_e32 v213, v213
	v_exp_f32_e32 v214, v214
	v_exp_f32_e32 v215, v215
	v_exp_f32_e32 v216, v216
	v_exp_f32_e32 v217, v217
	v_exp_f32_e32 v218, v218
	v_exp_f32_e32 v219, v219
	v_exp_f32_e32 v220, v220
	v_exp_f32_e32 v221, v221
	v_exp_f32_e32 v222, v222
	v_exp_f32_e32 v223, v223
	v_exp_f32_e32 v96, v96
	v_exp_f32_e32 v97, v97
	v_exp_f32_e32 v98, v98
	v_exp_f32_e32 v99, v99
	v_exp_f32_e32 v100, v100
	v_exp_f32_e32 v101, v101
	v_exp_f32_e32 v102, v102
	v_exp_f32_e32 v103, v103
	v_exp_f32_e32 v104, v104
	v_exp_f32_e32 v105, v105
	v_exp_f32_e32 v106, v106
	v_exp_f32_e32 v107, v107
	v_exp_f32_e32 v108, v108
	v_exp_f32_e32 v109, v109
	v_exp_f32_e32 v110, v110
	v_exp_f32_e32 v111, v111
	v_add_f32_e32 v12, v160, v161
	v_add_f32_e32 v13, v162, v163
	v_add_f32_e32 v14, v164, v165
	v_add_f32_e32 v15, v166, v167
	v_add_f32_e32 v12, v168, v12
	v_add_f32_e32 v13, v169, v13
	v_add_f32_e32 v14, v170, v14
	v_add_f32_e32 v15, v171, v15
	v_add_f32_e32 v12, v172, v12
	v_add_f32_e32 v13, v173, v13
	v_add_f32_e32 v14, v174, v14
	v_add_f32_e32 v15, v175, v15
	v_add_f32_e32 v12, v176, v12
	v_add_f32_e32 v13, v177, v13
	v_add_f32_e32 v14, v178, v14
	v_add_f32_e32 v15, v179, v15
	v_add_f32_e32 v12, v180, v12
	v_add_f32_e32 v13, v181, v13
	v_add_f32_e32 v14, v182, v14
	v_add_f32_e32 v15, v183, v15
	v_add_f32_e32 v12, v184, v12
	v_add_f32_e32 v13, v185, v13
	v_add_f32_e32 v14, v186, v14
	v_add_f32_e32 v15, v187, v15
	v_add_f32_e32 v12, v188, v12
	v_add_f32_e32 v13, v189, v13
	v_add_f32_e32 v14, v190, v14
	v_add_f32_e32 v15, v191, v15
	v_add_f32_e32 v12, v192, v12
	v_add_f32_e32 v13, v193, v13
	v_add_f32_e32 v14, v194, v14
	v_add_f32_e32 v15, v195, v15
	v_add_f32_e32 v12, v196, v12
	v_add_f32_e32 v13, v197, v13
	v_add_f32_e32 v14, v198, v14
	v_add_f32_e32 v15, v199, v15
	v_add_f32_e32 v12, v200, v12
	v_add_f32_e32 v13, v201, v13
	v_add_f32_e32 v14, v202, v14
	v_add_f32_e32 v15, v203, v15
	v_add_f32_e32 v12, v204, v12
	v_add_f32_e32 v13, v205, v13
	v_add_f32_e32 v14, v206, v14
	v_add_f32_e32 v15, v207, v15
	v_add_f32_e32 v12, v208, v12
	v_add_f32_e32 v13, v209, v13
	v_add_f32_e32 v14, v210, v14
	v_add_f32_e32 v15, v211, v15
	v_add_f32_e32 v12, v212, v12
	v_add_f32_e32 v13, v213, v13
	v_add_f32_e32 v14, v214, v14
	v_add_f32_e32 v15, v215, v15
	v_add_f32_e32 v12, v216, v12
	v_add_f32_e32 v13, v217, v13
	v_add_f32_e32 v14, v218, v14
	v_add_f32_e32 v15, v219, v15
	v_add_f32_e32 v12, v220, v12
	v_add_f32_e32 v13, v221, v13
	v_add_f32_e32 v14, v222, v14
	v_add_f32_e32 v15, v223, v15
	v_add_f32_e32 v12, v96, v12
	v_add_f32_e32 v13, v97, v13
	v_add_f32_e32 v14, v98, v14
	v_add_f32_e32 v15, v99, v15
	v_add_f32_e32 v12, v100, v12
	v_add_f32_e32 v13, v101, v13
	v_add_f32_e32 v14, v102, v14
	v_add_f32_e32 v15, v103, v15
	v_add_f32_e32 v12, v104, v12
	v_add_f32_e32 v13, v105, v13
	v_add_f32_e32 v14, v106, v14
	v_add_f32_e32 v15, v107, v15
	v_add_f32_e32 v12, v108, v12
	v_add_f32_e32 v13, v109, v13
	v_add_f32_e32 v14, v110, v14
	v_add_f32_e32 v15, v111, v15
	v_add_f32_e32 v12, v12, v13
	v_add_f32_e32 v14, v14, v15
	v_add_f32_e32 v6, v12, v14
	v_cvt_pk_bf16_f32 v160, v160, v161
	v_cvt_pk_bf16_f32 v161, v162, v163
	v_cvt_pk_bf16_f32 v162, v164, v165
	v_cvt_pk_bf16_f32 v163, v166, v167
	v_cvt_pk_bf16_f32 v164, v168, v169
	v_cvt_pk_bf16_f32 v165, v170, v171
	v_cvt_pk_bf16_f32 v166, v172, v173
	v_cvt_pk_bf16_f32 v167, v174, v175
	v_cvt_pk_bf16_f32 v176, v176, v177
	v_cvt_pk_bf16_f32 v177, v178, v179
	v_cvt_pk_bf16_f32 v178, v180, v181
	v_cvt_pk_bf16_f32 v179, v182, v183
	v_cvt_pk_bf16_f32 v180, v184, v185
	v_cvt_pk_bf16_f32 v181, v186, v187
	v_cvt_pk_bf16_f32 v182, v188, v189
	v_cvt_pk_bf16_f32 v183, v190, v191
	v_cvt_pk_bf16_f32 v192, v192, v193
	v_cvt_pk_bf16_f32 v193, v194, v195
	v_cvt_pk_bf16_f32 v194, v196, v197
	v_cvt_pk_bf16_f32 v195, v198, v199
	v_cvt_pk_bf16_f32 v196, v200, v201
	v_cvt_pk_bf16_f32 v197, v202, v203
	v_cvt_pk_bf16_f32 v198, v204, v205
	v_cvt_pk_bf16_f32 v199, v206, v207
	v_cvt_pk_bf16_f32 v208, v208, v209
	v_cvt_pk_bf16_f32 v209, v210, v211
	v_cvt_pk_bf16_f32 v210, v212, v213
	v_cvt_pk_bf16_f32 v211, v214, v215
	v_cvt_pk_bf16_f32 v212, v216, v217
	v_cvt_pk_bf16_f32 v213, v218, v219
	v_cvt_pk_bf16_f32 v214, v220, v221
	v_cvt_pk_bf16_f32 v215, v222, v223
	v_cvt_pk_bf16_f32 v96, v96, v97
	v_cvt_pk_bf16_f32 v97, v98, v99
	v_cvt_pk_bf16_f32 v98, v100, v101
	v_cvt_pk_bf16_f32 v99, v102, v103
	v_cvt_pk_bf16_f32 v100, v104, v105
	v_cvt_pk_bf16_f32 v101, v106, v107
	v_cvt_pk_bf16_f32 v102, v108, v109
	v_cvt_pk_bf16_f32 v103, v110, v111
	s_add_i32 s68, s72, 16
	s_and_b32 s68, s68, 15
	s_lshl_b32 s68, s68, 13
	v_add_u32_e32 v158, s68, v152
	ds_read_b128 v[48:51], v158 offset:4096
	ds_read_b128 v[52:55], v158 offset:5120
	ds_read_b128 v[56:59], v158 offset:6144
	ds_read_b128 v[60:63], v158 offset:7168
	s_waitcnt lgkmcnt(3)
	v_mfma_f32_32x32x16_bf16 v[32:47], v[48:51], v[96:99], 0
	s_waitcnt lgkmcnt(1)
	v_mfma_f32_32x32x16_bf16 v[16:31], v[56:59], v[96:99], 0
	v_mfma_f32_32x32x16_bf16 v[32:47], v[52:55], v[100:103], v[32:47]
	s_waitcnt lgkmcnt(0)
	v_mfma_f32_32x32x16_bf16 v[16:31], v[60:63], v[100:103], v[16:31]
	s_cmp_lt_i32 s85, 4
	s_cbranch_scc1 .La0_pvskip0
	s_add_i32 s68, s72, 12
	s_and_b32 s68, s68, 15
	s_lshl_b32 s68, s68, 13
	v_add_u32_e32 v158, s68, v152
	ds_read_b128 v[224:227], v158 offset:4096
	ds_read_b128 v[228:231], v158 offset:5120
	ds_read_b128 v[2:5], v158 offset:6144
	ds_read_b128 v[8:11], v158 offset:7168
	s_waitcnt lgkmcnt(3)
	v_mfma_f32_32x32x16_bf16 v[32:47], v[224:227], v[160:163], v[32:47]
	s_waitcnt lgkmcnt(1)
	v_mfma_f32_32x32x16_bf16 v[16:31], v[2:5], v[160:163], v[16:31]
	v_mfma_f32_32x32x16_bf16 v[32:47], v[228:231], v[164:167], v[32:47]
	s_waitcnt lgkmcnt(0)
	v_mfma_f32_32x32x16_bf16 v[16:31], v[8:11], v[164:167], v[16:31]
.La0_pvskip0:
	s_cmp_lt_i32 s85, 3
	s_cbranch_scc1 .La0_pvskip1
	s_add_i32 s68, s72, 13
	s_and_b32 s68, s68, 15
	s_lshl_b32 s68, s68, 13
	v_add_u32_e32 v158, s68, v152
	ds_read_b128 v[48:51], v158 offset:4096
	ds_read_b128 v[52:55], v158 offset:5120
	ds_read_b128 v[56:59], v158 offset:6144
	ds_read_b128 v[60:63], v158 offset:7168
	s_waitcnt lgkmcnt(3)
	v_mfma_f32_32x32x16_bf16 v[32:47], v[48:51], v[176:179], v[32:47]
	s_waitcnt lgkmcnt(1)
	v_mfma_f32_32x32x16_bf16 v[16:31], v[56:59], v[176:179], v[16:31]
	v_mfma_f32_32x32x16_bf16 v[32:47], v[52:55], v[180:183], v[32:47]
	s_waitcnt lgkmcnt(0)
	v_mfma_f32_32x32x16_bf16 v[16:31], v[60:63], v[180:183], v[16:31]
.La0_pvskip1:
	s_cmp_lt_i32 s85, 2
	s_cbranch_scc1 .La0_pvskip2
	s_add_i32 s68, s72, 14
	s_and_b32 s68, s68, 15
	s_lshl_b32 s68, s68, 13
	v_add_u32_e32 v158, s68, v152
	ds_read_b128 v[224:227], v158 offset:4096
	ds_read_b128 v[228:231], v158 offset:5120
	ds_read_b128 v[2:5], v158 offset:6144
	ds_read_b128 v[8:11], v158 offset:7168
	s_waitcnt lgkmcnt(3)
	v_mfma_f32_32x32x16_bf16 v[32:47], v[224:227], v[192:195], v[32:47]
	s_waitcnt lgkmcnt(1)
	v_mfma_f32_32x32x16_bf16 v[16:31], v[2:5], v[192:195], v[16:31]
	v_mfma_f32_32x32x16_bf16 v[32:47], v[228:231], v[196:199], v[32:47]
	s_waitcnt lgkmcnt(0)
	v_mfma_f32_32x32x16_bf16 v[16:31], v[8:11], v[196:199], v[16:31]
.La0_pvskip2:
	s_cmp_lt_i32 s85, 1
	s_cbranch_scc1 .La0_pvskip3
	s_add_i32 s68, s72, 15
	s_and_b32 s68, s68, 15
	s_lshl_b32 s68, s68, 13
	v_add_u32_e32 v158, s68, v152
	ds_read_b128 v[48:51], v158 offset:4096
	ds_read_b128 v[52:55], v158 offset:5120
	ds_read_b128 v[56:59], v158 offset:6144
	ds_read_b128 v[60:63], v158 offset:7168
	s_waitcnt lgkmcnt(3)
	v_mfma_f32_32x32x16_bf16 v[32:47], v[48:51], v[208:211], v[32:47]
	s_waitcnt lgkmcnt(1)
	v_mfma_f32_32x32x16_bf16 v[16:31], v[56:59], v[208:211], v[16:31]
	v_mfma_f32_32x32x16_bf16 v[32:47], v[52:55], v[212:215], v[32:47]
	s_waitcnt lgkmcnt(0)
	v_mfma_f32_32x32x16_bf16 v[16:31], v[60:63], v[212:215], v[16:31]
.La0_pvskip3:
	s_nop 7
	s_nop 4
